# grid barrier: member blocks poll the top-level generation word directly instead of the per-XCD relay word (one fewer hop per barrier)
# speedup vs baseline: 1.0060x; 1.0060x over previous
; __device__ __forceinline__ unsigned xb_ld(unsigned* p) { return __hip_atomic_load(p, __ATOMIC_RELAXED, __HIP_MEMORY_SCOPE_AGENT); }
; __device__ __forceinline__ unsigned xb_add(unsigned* p, unsigned v) { return __hip_atomic_fetch_add(p, v, __ATOMIC_RELAXED, __HIP_MEMORY_SCOPE_AGENT); }
; #define XB_SPIN(cond, bar) do { unsigned _sp = 0; while (cond) { __builtin_amdgcn_s_sleep(1); \
;     if ((++_sp & 255u) == 0u) { if (xb_ld(&(bar)[XB_TMO])) break; if (_sp > XB_SPIN_CAP) { atomicAdd(&(bar)[XB_TMO], 1u); break; } } } } while (0)
; __device__ __forceinline__ void xcd_barrier(const XcdBarrier& b) {
;     ...
;     const unsigned old = xb_add(&bar[XB_XSUB(b.x)], 1u);
;     const unsigned gen = old / nloc;
;     if (old + 1u == (gen + 1u) * nloc) {
;       __builtin_amdgcn_fence(__ATOMIC_RELEASE, "agent");
;       asm volatile("s_waitcnt vmcnt(0)" ::: "memory");
;       const unsigned og = xb_add(&bar[XB_TOP], 1u);
;       const unsigned tg = og / nx;
;       if (og + 1u == (tg + 1u) * nx) xb_add(&bar[XB_TOPGEN], 1u);
;       else XB_SPIN(xb_ld(&bar[XB_TOPGEN]) == tg, bar);
;       __builtin_amdgcn_fence(__ATOMIC_ACQUIRE, "agent");
;       xb_add(&bar[XB_XGEN(b.x)], 1u);
;       asm volatile("s_waitcnt vmcnt(0)" ::: "memory");
;     } else {
;       XB_SPIN(xb_ld(&bar[XB_XGEN(b.x)]) == gen, bar);
.LBB0_1345:
	s_or_b64 exec, exec, s[2:3]
	v_cvt_f32_u32_e32 v4, v2
	s_waitcnt vmcnt(0)
	v_readfirstlane_b32 s2, v3
	v_sub_u32_e32 v3, 0, v2
	v_rcp_iflag_f32_e32 v4, v4
	v_add_u32_e32 v5, s2, v1
	v_mul_f32_e32 v4, 0x4f7ffffe, v4
	v_cvt_u32_f32_e32 v4, v4
	v_mul_lo_u32 v1, v3, v4
	v_mul_hi_u32 v1, v4, v1
	v_add_u32_e32 v1, v4, v1
	v_mul_hi_u32 v1, v5, v1
	v_mul_lo_u32 v3, v1, v2
	v_sub_u32_e32 v3, v5, v3
	v_add_u32_e32 v4, 1, v1
	v_cmp_ge_u32_e32 vcc, v3, v2
	s_nop 1
	v_cndmask_b32_e32 v1, v1, v4, vcc
	v_sub_u32_e32 v4, v3, v2
	v_cndmask_b32_e32 v3, v3, v4, vcc
	v_add_u32_e32 v4, 1, v1
	v_cmp_ge_u32_e32 vcc, v3, v2
	v_add_u32_e32 v3, 1, v5
	s_nop 0
	v_cndmask_b32_e32 v1, v1, v4, vcc
	v_mul_lo_u32 v4, v2, v1
	v_add_u32_e32 v2, v4, v2
	v_cmp_ne_u32_e32 vcc, v3, v2
	s_and_saveexec_b64 s[2:3], vcc
	s_xor_b64 s[2:3], exec, s[2:3]
	s_cbranch_execz .LBB0_1359
	v_readlane_b32 s0, v253, 43
	v_readlane_b32 s1, v253, 44
	s_waitcnt lgkmcnt(0)
	s_nop 3
	global_load_dword v0, v149, s[0:1] sc1
	s_waitcnt vmcnt(0)
	v_cmp_eq_u32_e32 vcc, v0, v1
	s_and_saveexec_b64 s[4:5], vcc
	s_cbranch_execz .LBB0_1358
	s_mov_b32 s10, 1
	s_mov_b64 s[12:13], 0
	s_branch .LBB0_1349

; __device__ __forceinline__ unsigned xb_ld(unsigned* p) { return __hip_atomic_load(p, __ATOMIC_RELAXED, __HIP_MEMORY_SCOPE_AGENT); }
; #define XB_SPIN(cond, bar) do { unsigned _sp = 0; while (cond) { __builtin_amdgcn_s_sleep(1); \
;     if ((++_sp & 255u) == 0u) { if (xb_ld(&(bar)[XB_TMO])) break; if (_sp > XB_SPIN_CAP) { atomicAdd(&(bar)[XB_TMO], 1u); break; } } } } while (0)
; __device__ __forceinline__ void xcd_barrier(const XcdBarrier& b) {
;     ...
;       XB_SPIN(xb_ld(&bar[XB_XGEN(b.x)]) == gen, bar);
.LBB0_1351:
	v_readlane_b32 s0, v253, 43
	v_readlane_b32 s1, v253, 44
	s_add_i32 s10, s10, 1
	s_mov_b64 s[36:37], -1
	s_nop 2
	global_load_dword v0, v149, s[0:1] sc1
	s_waitcnt vmcnt(0)
	v_cmp_ne_u32_e32 vcc, v0, v1
	s_orn2_b64 s[30:31], vcc, exec
	s_branch .LBB0_1348
